# gemm_in au/av column tiles: own gelu_tanh epilogue for both tiles with paired 16-byte stores
# baseline (speedup 1.0000x reference)
.Lg2_g8:
	s_cmp_lt_u32 s37, 8
	s_cbranch_scc0 .Lg2_2p
	s_and_b32 s3, s37, 3
	s_cmp_lt_u32 s37, 4
	s_cselect_b32 s2, 0, 8
	s_add_u32 s92, s84, s2
	s_addc_u32 s93, s85, 0
	s_load_dwordx2 s[92:93], s[92:93], 0x140
	v_lshrrev_b32_e32 v148, 7, v196
	v_and_b32_e32 v149, 15, v196
	v_lshl_or_b32 v148, v148, 6, v149
	v_bfe_u32 v149, v196, 6, 1
	v_bfe_u32 v150, v196, 4, 2
	v_lshlrev_b32_e32 v148, 10, v148
	v_lshlrev_b32_e32 v149, 7, v149
	v_lshl_or_b32 v149, v150, 3, v149
	v_and_b32_e32 v150, 1, v150
	v_mul_u32_u24_e32 v150, 24, v150
	v_add3_u32 v156, v148, v149, v150
	v_add_u32_e32 v157, 0x4000, v156
	v_add_u32_e32 v158, 0x8000, v156
	v_add_u32_e32 v159, 0xc000, v156
	s_waitcnt lgkmcnt(0)
	s_lshl_b32 s2, s0, 17
	s_lshl_b32 s38, s3, 8
	s_add_i32 s2, s2, s38
	s_add_u32 s96, s92, s2
	s_addc_u32 s97, s93, 0
	v_mul_f32_e32 v148, 0x3d372713, v62
	v_mul_f32_e32 v149, 0x3d372713, v63
	v_mul_f32_e32 v150, 0x3d372713, v64
	v_mul_f32_e32 v151, 0x3d372713, v65
	v_mul_f32_e32 v148, v62, v148
	v_mul_f32_e32 v149, v63, v149
	v_mul_f32_e32 v150, v64, v150
	v_mul_f32_e32 v151, v65, v151
	v_fma_f32 v148, v62, v148, v62
	v_fma_f32 v149, v63, v149, v63
	v_fma_f32 v150, v64, v150, v64
	v_fma_f32 v151, v65, v151, v65
	v_mul_f32_e32 v148, 0x3f4c422a, v148
	v_mul_f32_e32 v149, 0x3f4c422a, v149
	v_mul_f32_e32 v150, 0x3f4c422a, v150
	v_mul_f32_e32 v151, 0x3f4c422a, v151
	v_add_f32_e32 v148, v148, v148
	v_add_f32_e32 v149, v149, v149
	v_add_f32_e32 v150, v150, v150
	v_add_f32_e32 v151, v151, v151
	v_mul_f32_e32 v148, 0xbfb8aa3b, v148
	v_mul_f32_e32 v149, 0xbfb8aa3b, v149
	v_mul_f32_e32 v150, 0xbfb8aa3b, v150
	v_mul_f32_e32 v151, 0xbfb8aa3b, v151
	v_exp_f32_e32 v148, v148
	v_exp_f32_e32 v149, v149
	v_exp_f32_e32 v150, v150
	v_exp_f32_e32 v151, v151
	v_add_f32_e32 v148, 1.0, v148
	v_add_f32_e32 v149, 1.0, v149
	v_add_f32_e32 v150, 1.0, v150
	v_add_f32_e32 v151, 1.0, v151
	v_rcp_f32_e32 v148, v148
	v_rcp_f32_e32 v149, v149
	v_rcp_f32_e32 v150, v150
	v_rcp_f32_e32 v151, v151
	s_nop 0
	v_pk_mul_f32 v[148:149], v[62:63], v[148:149]
	v_pk_mul_f32 v[150:151], v[64:65], v[150:151]
	v_cvt_pk_bf16_f32 v164, v148, v149
	v_cvt_pk_bf16_f32 v165, v150, v151
	v_mul_f32_e32 v148, 0x3d372713, v58
	v_mul_f32_e32 v149, 0x3d372713, v59
	v_mul_f32_e32 v150, 0x3d372713, v60
	v_mul_f32_e32 v151, 0x3d372713, v61
	v_mul_f32_e32 v148, v58, v148
	v_mul_f32_e32 v149, v59, v149
	v_mul_f32_e32 v150, v60, v150
	v_mul_f32_e32 v151, v61, v151
	v_fma_f32 v148, v58, v148, v58
	v_fma_f32 v149, v59, v149, v59
	v_fma_f32 v150, v60, v150, v60
	v_fma_f32 v151, v61, v151, v61
	v_mul_f32_e32 v148, 0x3f4c422a, v148
	v_mul_f32_e32 v149, 0x3f4c422a, v149
	v_mul_f32_e32 v150, 0x3f4c422a, v150
	v_mul_f32_e32 v151, 0x3f4c422a, v151
	v_add_f32_e32 v148, v148, v148
	v_add_f32_e32 v149, v149, v149
	v_add_f32_e32 v150, v150, v150
	v_add_f32_e32 v151, v151, v151
	v_mul_f32_e32 v148, 0xbfb8aa3b, v148
	v_mul_f32_e32 v149, 0xbfb8aa3b, v149
	v_mul_f32_e32 v150, 0xbfb8aa3b, v150
	v_mul_f32_e32 v151, 0xbfb8aa3b, v151
	v_exp_f32_e32 v148, v148
	v_exp_f32_e32 v149, v149
	v_exp_f32_e32 v150, v150
	v_exp_f32_e32 v151, v151
	v_add_f32_e32 v148, 1.0, v148
	v_add_f32_e32 v149, 1.0, v149
	v_add_f32_e32 v150, 1.0, v150
	v_add_f32_e32 v151, 1.0, v151
	v_rcp_f32_e32 v148, v148
	v_rcp_f32_e32 v149, v149
	v_rcp_f32_e32 v150, v150
	v_rcp_f32_e32 v151, v151
	s_nop 0
	v_pk_mul_f32 v[148:149], v[58:59], v[148:149]
	v_pk_mul_f32 v[150:151], v[60:61], v[150:151]
	v_cvt_pk_bf16_f32 v166, v148, v149
	v_cvt_pk_bf16_f32 v167, v150, v151
	s_nop 1
	v_permlane16_swap_b32 v164, v166
	v_permlane16_swap_b32 v165, v167
	s_nop 1
	global_store_dwordx4 v156, v[164:167], s[96:97]
	v_mul_f32_e32 v148, 0x3d372713, v54
	v_mul_f32_e32 v149, 0x3d372713, v55
	v_mul_f32_e32 v150, 0x3d372713, v56
	v_mul_f32_e32 v151, 0x3d372713, v57
	v_mul_f32_e32 v148, v54, v148
	v_mul_f32_e32 v149, v55, v149
	v_mul_f32_e32 v150, v56, v150
	v_mul_f32_e32 v151, v57, v151
	v_fma_f32 v148, v54, v148, v54
	v_fma_f32 v149, v55, v149, v55
	v_fma_f32 v150, v56, v150, v56
	v_fma_f32 v151, v57, v151, v57
	v_mul_f32_e32 v148, 0x3f4c422a, v148
	v_mul_f32_e32 v149, 0x3f4c422a, v149
	v_mul_f32_e32 v150, 0x3f4c422a, v150
	v_mul_f32_e32 v151, 0x3f4c422a, v151
	v_add_f32_e32 v148, v148, v148
	v_add_f32_e32 v149, v149, v149
	v_add_f32_e32 v150, v150, v150
	v_add_f32_e32 v151, v151, v151
	v_mul_f32_e32 v148, 0xbfb8aa3b, v148
	v_mul_f32_e32 v149, 0xbfb8aa3b, v149
	v_mul_f32_e32 v150, 0xbfb8aa3b, v150
	v_mul_f32_e32 v151, 0xbfb8aa3b, v151
	v_exp_f32_e32 v148, v148
	v_exp_f32_e32 v149, v149
	v_exp_f32_e32 v150, v150
	v_exp_f32_e32 v151, v151
	v_add_f32_e32 v148, 1.0, v148
	v_add_f32_e32 v149, 1.0, v149
	v_add_f32_e32 v150, 1.0, v150
	v_add_f32_e32 v151, 1.0, v151
	v_rcp_f32_e32 v148, v148
	v_rcp_f32_e32 v149, v149
	v_rcp_f32_e32 v150, v150
	v_rcp_f32_e32 v151, v151
	s_nop 0
	v_pk_mul_f32 v[148:149], v[54:55], v[148:149]
	v_pk_mul_f32 v[150:151], v[56:57], v[150:151]
	v_cvt_pk_bf16_f32 v168, v148, v149
	v_cvt_pk_bf16_f32 v169, v150, v151
	v_mul_f32_e32 v148, 0x3d372713, v50
	v_mul_f32_e32 v149, 0x3d372713, v51
	v_mul_f32_e32 v150, 0x3d372713, v52
	v_mul_f32_e32 v151, 0x3d372713, v53
	v_mul_f32_e32 v148, v50, v148
	v_mul_f32_e32 v149, v51, v149
	v_mul_f32_e32 v150, v52, v150
	v_mul_f32_e32 v151, v53, v151
	v_fma_f32 v148, v50, v148, v50
	v_fma_f32 v149, v51, v149, v51
	v_fma_f32 v150, v52, v150, v52
	v_fma_f32 v151, v53, v151, v53
	v_mul_f32_e32 v148, 0x3f4c422a, v148
	v_mul_f32_e32 v149, 0x3f4c422a, v149
	v_mul_f32_e32 v150, 0x3f4c422a, v150
	v_mul_f32_e32 v151, 0x3f4c422a, v151
	v_add_f32_e32 v148, v148, v148
	v_add_f32_e32 v149, v149, v149
	v_add_f32_e32 v150, v150, v150
	v_add_f32_e32 v151, v151, v151
	v_mul_f32_e32 v148, 0xbfb8aa3b, v148
	v_mul_f32_e32 v149, 0xbfb8aa3b, v149
	v_mul_f32_e32 v150, 0xbfb8aa3b, v150
	v_mul_f32_e32 v151, 0xbfb8aa3b, v151
	v_exp_f32_e32 v148, v148
	v_exp_f32_e32 v149, v149
	v_exp_f32_e32 v150, v150
	v_exp_f32_e32 v151, v151
	v_add_f32_e32 v148, 1.0, v148
	v_add_f32_e32 v149, 1.0, v149
	v_add_f32_e32 v150, 1.0, v150
	v_add_f32_e32 v151, 1.0, v151
	v_rcp_f32_e32 v148, v148
	v_rcp_f32_e32 v149, v149
	v_rcp_f32_e32 v150, v150
	v_rcp_f32_e32 v151, v151
	s_nop 0
	v_pk_mul_f32 v[148:149], v[50:51], v[148:149]
	v_pk_mul_f32 v[150:151], v[52:53], v[150:151]
	v_cvt_pk_bf16_f32 v170, v148, v149
	v_cvt_pk_bf16_f32 v171, v150, v151
	s_nop 1
	v_permlane16_swap_b32 v168, v170
	v_permlane16_swap_b32 v169, v171
	s_nop 1
	global_store_dwordx4 v156, v[168:171], s[96:97] offset:64
	v_mul_f32_e32 v148, 0x3d372713, v46
	v_mul_f32_e32 v149, 0x3d372713, v47
	v_mul_f32_e32 v150, 0x3d372713, v48
	v_mul_f32_e32 v151, 0x3d372713, v49
	v_mul_f32_e32 v148, v46, v148
	v_mul_f32_e32 v149, v47, v149
	v_mul_f32_e32 v150, v48, v150
	v_mul_f32_e32 v151, v49, v151
	v_fma_f32 v148, v46, v148, v46
	v_fma_f32 v149, v47, v149, v47
	v_fma_f32 v150, v48, v150, v48
	v_fma_f32 v151, v49, v151, v49
	v_mul_f32_e32 v148, 0x3f4c422a, v148
	v_mul_f32_e32 v149, 0x3f4c422a, v149
	v_mul_f32_e32 v150, 0x3f4c422a, v150
	v_mul_f32_e32 v151, 0x3f4c422a, v151
	v_add_f32_e32 v148, v148, v148
	v_add_f32_e32 v149, v149, v149
	v_add_f32_e32 v150, v150, v150
	v_add_f32_e32 v151, v151, v151
	v_mul_f32_e32 v148, 0xbfb8aa3b, v148
	v_mul_f32_e32 v149, 0xbfb8aa3b, v149
	v_mul_f32_e32 v150, 0xbfb8aa3b, v150
	v_mul_f32_e32 v151, 0xbfb8aa3b, v151
	v_exp_f32_e32 v148, v148
	v_exp_f32_e32 v149, v149
	v_exp_f32_e32 v150, v150
	v_exp_f32_e32 v151, v151
	v_add_f32_e32 v148, 1.0, v148
	v_add_f32_e32 v149, 1.0, v149
	v_add_f32_e32 v150, 1.0, v150
	v_add_f32_e32 v151, 1.0, v151
	v_rcp_f32_e32 v148, v148
	v_rcp_f32_e32 v149, v149
	v_rcp_f32_e32 v150, v150
	v_rcp_f32_e32 v151, v151
	s_nop 0
	v_pk_mul_f32 v[148:149], v[46:47], v[148:149]
	v_pk_mul_f32 v[150:151], v[48:49], v[150:151]
	v_cvt_pk_bf16_f32 v164, v148, v149
	v_cvt_pk_bf16_f32 v165, v150, v151
	v_mul_f32_e32 v148, 0x3d372713, v42
	v_mul_f32_e32 v149, 0x3d372713, v43
	v_mul_f32_e32 v150, 0x3d372713, v44
	v_mul_f32_e32 v151, 0x3d372713, v45
	v_mul_f32_e32 v148, v42, v148
	v_mul_f32_e32 v149, v43, v149
	v_mul_f32_e32 v150, v44, v150
	v_mul_f32_e32 v151, v45, v151
	v_fma_f32 v148, v42, v148, v42
	v_fma_f32 v149, v43, v149, v43
	v_fma_f32 v150, v44, v150, v44
	v_fma_f32 v151, v45, v151, v45
	v_mul_f32_e32 v148, 0x3f4c422a, v148
	v_mul_f32_e32 v149, 0x3f4c422a, v149
	v_mul_f32_e32 v150, 0x3f4c422a, v150
	v_mul_f32_e32 v151, 0x3f4c422a, v151
	v_add_f32_e32 v148, v148, v148
	v_add_f32_e32 v149, v149, v149
	v_add_f32_e32 v150, v150, v150
	v_add_f32_e32 v151, v151, v151
	v_mul_f32_e32 v148, 0xbfb8aa3b, v148
	v_mul_f32_e32 v149, 0xbfb8aa3b, v149
	v_mul_f32_e32 v150, 0xbfb8aa3b, v150
	v_mul_f32_e32 v151, 0xbfb8aa3b, v151
	v_exp_f32_e32 v148, v148
	v_exp_f32_e32 v149, v149
	v_exp_f32_e32 v150, v150
	v_exp_f32_e32 v151, v151
	v_add_f32_e32 v148, 1.0, v148
	v_add_f32_e32 v149, 1.0, v149
	v_add_f32_e32 v150, 1.0, v150
	v_add_f32_e32 v151, 1.0, v151
	v_rcp_f32_e32 v148, v148
	v_rcp_f32_e32 v149, v149
	v_rcp_f32_e32 v150, v150
	v_rcp_f32_e32 v151, v151
	s_nop 0
	v_pk_mul_f32 v[148:149], v[42:43], v[148:149]
	v_pk_mul_f32 v[150:151], v[44:45], v[150:151]
	v_cvt_pk_bf16_f32 v166, v148, v149
	v_cvt_pk_bf16_f32 v167, v150, v151
	s_nop 1
	v_permlane16_swap_b32 v164, v166
	v_permlane16_swap_b32 v165, v167
	s_nop 1
	global_store_dwordx4 v157, v[164:167], s[96:97]
	v_mul_f32_e32 v148, 0x3d372713, v38
	v_mul_f32_e32 v149, 0x3d372713, v39
	v_mul_f32_e32 v150, 0x3d372713, v40
	v_mul_f32_e32 v151, 0x3d372713, v41
	v_mul_f32_e32 v148, v38, v148
	v_mul_f32_e32 v149, v39, v149
	v_mul_f32_e32 v150, v40, v150
	v_mul_f32_e32 v151, v41, v151
	v_fma_f32 v148, v38, v148, v38
	v_fma_f32 v149, v39, v149, v39
	v_fma_f32 v150, v40, v150, v40
	v_fma_f32 v151, v41, v151, v41
	v_mul_f32_e32 v148, 0x3f4c422a, v148
	v_mul_f32_e32 v149, 0x3f4c422a, v149
	v_mul_f32_e32 v150, 0x3f4c422a, v150
	v_mul_f32_e32 v151, 0x3f4c422a, v151
	v_add_f32_e32 v148, v148, v148
	v_add_f32_e32 v149, v149, v149
	v_add_f32_e32 v150, v150, v150
	v_add_f32_e32 v151, v151, v151
	v_mul_f32_e32 v148, 0xbfb8aa3b, v148
	v_mul_f32_e32 v149, 0xbfb8aa3b, v149
	v_mul_f32_e32 v150, 0xbfb8aa3b, v150
	v_mul_f32_e32 v151, 0xbfb8aa3b, v151
	v_exp_f32_e32 v148, v148
	v_exp_f32_e32 v149, v149
	v_exp_f32_e32 v150, v150
	v_exp_f32_e32 v151, v151
	v_add_f32_e32 v148, 1.0, v148
	v_add_f32_e32 v149, 1.0, v149
	v_add_f32_e32 v150, 1.0, v150
	v_add_f32_e32 v151, 1.0, v151
	v_rcp_f32_e32 v148, v148
	v_rcp_f32_e32 v149, v149
	v_rcp_f32_e32 v150, v150
	v_rcp_f32_e32 v151, v151
	s_nop 0
	v_pk_mul_f32 v[148:149], v[38:39], v[148:149]
	v_pk_mul_f32 v[150:151], v[40:41], v[150:151]
	v_cvt_pk_bf16_f32 v168, v148, v149
	v_cvt_pk_bf16_f32 v169, v150, v151
	v_mul_f32_e32 v148, 0x3d372713, v34
	v_mul_f32_e32 v149, 0x3d372713, v35
	v_mul_f32_e32 v150, 0x3d372713, v36
	v_mul_f32_e32 v151, 0x3d372713, v37
	v_mul_f32_e32 v148, v34, v148
	v_mul_f32_e32 v149, v35, v149
	v_mul_f32_e32 v150, v36, v150
	v_mul_f32_e32 v151, v37, v151
	v_fma_f32 v148, v34, v148, v34
	v_fma_f32 v149, v35, v149, v35
	v_fma_f32 v150, v36, v150, v36
	v_fma_f32 v151, v37, v151, v37
	v_mul_f32_e32 v148, 0x3f4c422a, v148
	v_mul_f32_e32 v149, 0x3f4c422a, v149
	v_mul_f32_e32 v150, 0x3f4c422a, v150
	v_mul_f32_e32 v151, 0x3f4c422a, v151
	v_add_f32_e32 v148, v148, v148
	v_add_f32_e32 v149, v149, v149
	v_add_f32_e32 v150, v150, v150
	v_add_f32_e32 v151, v151, v151
	v_mul_f32_e32 v148, 0xbfb8aa3b, v148
	v_mul_f32_e32 v149, 0xbfb8aa3b, v149
	v_mul_f32_e32 v150, 0xbfb8aa3b, v150
	v_mul_f32_e32 v151, 0xbfb8aa3b, v151
	v_exp_f32_e32 v148, v148
	v_exp_f32_e32 v149, v149
	v_exp_f32_e32 v150, v150
	v_exp_f32_e32 v151, v151
	v_add_f32_e32 v148, 1.0, v148
	v_add_f32_e32 v149, 1.0, v149
	v_add_f32_e32 v150, 1.0, v150
	v_add_f32_e32 v151, 1.0, v151
	v_rcp_f32_e32 v148, v148
	v_rcp_f32_e32 v149, v149
	v_rcp_f32_e32 v150, v150
	v_rcp_f32_e32 v151, v151
	s_nop 0
	v_pk_mul_f32 v[148:149], v[34:35], v[148:149]
	v_pk_mul_f32 v[150:151], v[36:37], v[150:151]
	v_cvt_pk_bf16_f32 v170, v148, v149
	v_cvt_pk_bf16_f32 v171, v150, v151
	s_nop 1
	v_permlane16_swap_b32 v168, v170
	v_permlane16_swap_b32 v169, v171
	s_nop 1
	global_store_dwordx4 v157, v[168:171], s[96:97] offset:64
	v_mul_f32_e32 v148, 0x3d372713, v30
	v_mul_f32_e32 v149, 0x3d372713, v31
	v_mul_f32_e32 v150, 0x3d372713, v32
	v_mul_f32_e32 v151, 0x3d372713, v33
	v_mul_f32_e32 v148, v30, v148
	v_mul_f32_e32 v149, v31, v149
	v_mul_f32_e32 v150, v32, v150
	v_mul_f32_e32 v151, v33, v151
	v_fma_f32 v148, v30, v148, v30
	v_fma_f32 v149, v31, v149, v31
	v_fma_f32 v150, v32, v150, v32
	v_fma_f32 v151, v33, v151, v33
	v_mul_f32_e32 v148, 0x3f4c422a, v148
	v_mul_f32_e32 v149, 0x3f4c422a, v149
	v_mul_f32_e32 v150, 0x3f4c422a, v150
	v_mul_f32_e32 v151, 0x3f4c422a, v151
	v_add_f32_e32 v148, v148, v148
	v_add_f32_e32 v149, v149, v149
	v_add_f32_e32 v150, v150, v150
	v_add_f32_e32 v151, v151, v151
	v_mul_f32_e32 v148, 0xbfb8aa3b, v148
	v_mul_f32_e32 v149, 0xbfb8aa3b, v149
	v_mul_f32_e32 v150, 0xbfb8aa3b, v150
	v_mul_f32_e32 v151, 0xbfb8aa3b, v151
	v_exp_f32_e32 v148, v148
	v_exp_f32_e32 v149, v149
	v_exp_f32_e32 v150, v150
	v_exp_f32_e32 v151, v151
	v_add_f32_e32 v148, 1.0, v148
	v_add_f32_e32 v149, 1.0, v149
	v_add_f32_e32 v150, 1.0, v150
	v_add_f32_e32 v151, 1.0, v151
	v_rcp_f32_e32 v148, v148
	v_rcp_f32_e32 v149, v149
	v_rcp_f32_e32 v150, v150
	v_rcp_f32_e32 v151, v151
	s_nop 0
	v_pk_mul_f32 v[148:149], v[30:31], v[148:149]
	v_pk_mul_f32 v[150:151], v[32:33], v[150:151]
	v_cvt_pk_bf16_f32 v164, v148, v149
	v_cvt_pk_bf16_f32 v165, v150, v151
	v_mul_f32_e32 v148, 0x3d372713, v26
	v_mul_f32_e32 v149, 0x3d372713, v27
	v_mul_f32_e32 v150, 0x3d372713, v28
	v_mul_f32_e32 v151, 0x3d372713, v29
	v_mul_f32_e32 v148, v26, v148
	v_mul_f32_e32 v149, v27, v149
	v_mul_f32_e32 v150, v28, v150
	v_mul_f32_e32 v151, v29, v151
	v_fma_f32 v148, v26, v148, v26
	v_fma_f32 v149, v27, v149, v27
	v_fma_f32 v150, v28, v150, v28
	v_fma_f32 v151, v29, v151, v29
	v_mul_f32_e32 v148, 0x3f4c422a, v148
	v_mul_f32_e32 v149, 0x3f4c422a, v149
	v_mul_f32_e32 v150, 0x3f4c422a, v150
	v_mul_f32_e32 v151, 0x3f4c422a, v151
	v_add_f32_e32 v148, v148, v148
	v_add_f32_e32 v149, v149, v149
	v_add_f32_e32 v150, v150, v150
	v_add_f32_e32 v151, v151, v151
	v_mul_f32_e32 v148, 0xbfb8aa3b, v148
	v_mul_f32_e32 v149, 0xbfb8aa3b, v149
	v_mul_f32_e32 v150, 0xbfb8aa3b, v150
	v_mul_f32_e32 v151, 0xbfb8aa3b, v151
	v_exp_f32_e32 v148, v148
	v_exp_f32_e32 v149, v149
	v_exp_f32_e32 v150, v150
	v_exp_f32_e32 v151, v151
	v_add_f32_e32 v148, 1.0, v148
	v_add_f32_e32 v149, 1.0, v149
	v_add_f32_e32 v150, 1.0, v150
	v_add_f32_e32 v151, 1.0, v151
	v_rcp_f32_e32 v148, v148
	v_rcp_f32_e32 v149, v149
	v_rcp_f32_e32 v150, v150
	v_rcp_f32_e32 v151, v151
	s_nop 0
	v_pk_mul_f32 v[148:149], v[26:27], v[148:149]
	v_pk_mul_f32 v[150:151], v[28:29], v[150:151]
	v_cvt_pk_bf16_f32 v166, v148, v149
	v_cvt_pk_bf16_f32 v167, v150, v151
	s_nop 1
	v_permlane16_swap_b32 v164, v166
	v_permlane16_swap_b32 v165, v167
	s_nop 1
	global_store_dwordx4 v158, v[164:167], s[96:97]
	v_mul_f32_e32 v148, 0x3d372713, v22
	v_mul_f32_e32 v149, 0x3d372713, v23
	v_mul_f32_e32 v150, 0x3d372713, v24
	v_mul_f32_e32 v151, 0x3d372713, v25
	v_mul_f32_e32 v148, v22, v148
	v_mul_f32_e32 v149, v23, v149
	v_mul_f32_e32 v150, v24, v150
	v_mul_f32_e32 v151, v25, v151
	v_fma_f32 v148, v22, v148, v22
	v_fma_f32 v149, v23, v149, v23
	v_fma_f32 v150, v24, v150, v24
	v_fma_f32 v151, v25, v151, v25
	v_mul_f32_e32 v148, 0x3f4c422a, v148
	v_mul_f32_e32 v149, 0x3f4c422a, v149
	v_mul_f32_e32 v150, 0x3f4c422a, v150
	v_mul_f32_e32 v151, 0x3f4c422a, v151
	v_add_f32_e32 v148, v148, v148
	v_add_f32_e32 v149, v149, v149
	v_add_f32_e32 v150, v150, v150
	v_add_f32_e32 v151, v151, v151
	v_mul_f32_e32 v148, 0xbfb8aa3b, v148
	v_mul_f32_e32 v149, 0xbfb8aa3b, v149
	v_mul_f32_e32 v150, 0xbfb8aa3b, v150
	v_mul_f32_e32 v151, 0xbfb8aa3b, v151
	v_exp_f32_e32 v148, v148
	v_exp_f32_e32 v149, v149
	v_exp_f32_e32 v150, v150
	v_exp_f32_e32 v151, v151
	v_add_f32_e32 v148, 1.0, v148
	v_add_f32_e32 v149, 1.0, v149
	v_add_f32_e32 v150, 1.0, v150
	v_add_f32_e32 v151, 1.0, v151
	v_rcp_f32_e32 v148, v148
	v_rcp_f32_e32 v149, v149
	v_rcp_f32_e32 v150, v150
	v_rcp_f32_e32 v151, v151
	s_nop 0
	v_pk_mul_f32 v[148:149], v[22:23], v[148:149]
	v_pk_mul_f32 v[150:151], v[24:25], v[150:151]
	v_cvt_pk_bf16_f32 v168, v148, v149
	v_cvt_pk_bf16_f32 v169, v150, v151
	v_mul_f32_e32 v148, 0x3d372713, v18
	v_mul_f32_e32 v149, 0x3d372713, v19
	v_mul_f32_e32 v150, 0x3d372713, v20
	v_mul_f32_e32 v151, 0x3d372713, v21
	v_mul_f32_e32 v148, v18, v148
	v_mul_f32_e32 v149, v19, v149
	v_mul_f32_e32 v150, v20, v150
	v_mul_f32_e32 v151, v21, v151
	v_fma_f32 v148, v18, v148, v18
	v_fma_f32 v149, v19, v149, v19
	v_fma_f32 v150, v20, v150, v20
	v_fma_f32 v151, v21, v151, v21
	v_mul_f32_e32 v148, 0x3f4c422a, v148
	v_mul_f32_e32 v149, 0x3f4c422a, v149
	v_mul_f32_e32 v150, 0x3f4c422a, v150
	v_mul_f32_e32 v151, 0x3f4c422a, v151
	v_add_f32_e32 v148, v148, v148
	v_add_f32_e32 v149, v149, v149
	v_add_f32_e32 v150, v150, v150
	v_add_f32_e32 v151, v151, v151
	v_mul_f32_e32 v148, 0xbfb8aa3b, v148
	v_mul_f32_e32 v149, 0xbfb8aa3b, v149
	v_mul_f32_e32 v150, 0xbfb8aa3b, v150
	v_mul_f32_e32 v151, 0xbfb8aa3b, v151
	v_exp_f32_e32 v148, v148
	v_exp_f32_e32 v149, v149
	v_exp_f32_e32 v150, v150
	v_exp_f32_e32 v151, v151
	v_add_f32_e32 v148, 1.0, v148
	v_add_f32_e32 v149, 1.0, v149
	v_add_f32_e32 v150, 1.0, v150
	v_add_f32_e32 v151, 1.0, v151
	v_rcp_f32_e32 v148, v148
	v_rcp_f32_e32 v149, v149
	v_rcp_f32_e32 v150, v150
	v_rcp_f32_e32 v151, v151
	s_nop 0
	v_pk_mul_f32 v[148:149], v[18:19], v[148:149]
	v_pk_mul_f32 v[150:151], v[20:21], v[150:151]
	v_cvt_pk_bf16_f32 v170, v148, v149
	v_cvt_pk_bf16_f32 v171, v150, v151
	s_nop 1
	v_permlane16_swap_b32 v168, v170
	v_permlane16_swap_b32 v169, v171
	s_nop 1
	global_store_dwordx4 v158, v[168:171], s[96:97] offset:64
	v_mul_f32_e32 v148, 0x3d372713, v14
	v_mul_f32_e32 v149, 0x3d372713, v15
	v_mul_f32_e32 v150, 0x3d372713, v16
	v_mul_f32_e32 v151, 0x3d372713, v17
	v_mul_f32_e32 v148, v14, v148
	v_mul_f32_e32 v149, v15, v149
	v_mul_f32_e32 v150, v16, v150
	v_mul_f32_e32 v151, v17, v151
	v_fma_f32 v148, v14, v148, v14
	v_fma_f32 v149, v15, v149, v15
	v_fma_f32 v150, v16, v150, v16
	v_fma_f32 v151, v17, v151, v17
	v_mul_f32_e32 v148, 0x3f4c422a, v148
	v_mul_f32_e32 v149, 0x3f4c422a, v149
	v_mul_f32_e32 v150, 0x3f4c422a, v150
	v_mul_f32_e32 v151, 0x3f4c422a, v151
	v_add_f32_e32 v148, v148, v148
	v_add_f32_e32 v149, v149, v149
	v_add_f32_e32 v150, v150, v150
	v_add_f32_e32 v151, v151, v151
	v_mul_f32_e32 v148, 0xbfb8aa3b, v148
	v_mul_f32_e32 v149, 0xbfb8aa3b, v149
	v_mul_f32_e32 v150, 0xbfb8aa3b, v150
	v_mul_f32_e32 v151, 0xbfb8aa3b, v151
	v_exp_f32_e32 v148, v148
	v_exp_f32_e32 v149, v149
	v_exp_f32_e32 v150, v150
	v_exp_f32_e32 v151, v151
	v_add_f32_e32 v148, 1.0, v148
	v_add_f32_e32 v149, 1.0, v149
	v_add_f32_e32 v150, 1.0, v150
	v_add_f32_e32 v151, 1.0, v151
	v_rcp_f32_e32 v148, v148
	v_rcp_f32_e32 v149, v149
	v_rcp_f32_e32 v150, v150
	v_rcp_f32_e32 v151, v151
	s_nop 0
	v_pk_mul_f32 v[148:149], v[14:15], v[148:149]
	v_pk_mul_f32 v[150:151], v[16:17], v[150:151]
	v_cvt_pk_bf16_f32 v164, v148, v149
	v_cvt_pk_bf16_f32 v165, v150, v151
	v_mul_f32_e32 v148, 0x3d372713, v10
	v_mul_f32_e32 v149, 0x3d372713, v11
	v_mul_f32_e32 v150, 0x3d372713, v12
	v_mul_f32_e32 v151, 0x3d372713, v13
	v_mul_f32_e32 v148, v10, v148
	v_mul_f32_e32 v149, v11, v149
	v_mul_f32_e32 v150, v12, v150
	v_mul_f32_e32 v151, v13, v151
	v_fma_f32 v148, v10, v148, v10
	v_fma_f32 v149, v11, v149, v11
	v_fma_f32 v150, v12, v150, v12
	v_fma_f32 v151, v13, v151, v13
	v_mul_f32_e32 v148, 0x3f4c422a, v148
	v_mul_f32_e32 v149, 0x3f4c422a, v149
	v_mul_f32_e32 v150, 0x3f4c422a, v150
	v_mul_f32_e32 v151, 0x3f4c422a, v151
	v_add_f32_e32 v148, v148, v148
	v_add_f32_e32 v149, v149, v149
	v_add_f32_e32 v150, v150, v150
	v_add_f32_e32 v151, v151, v151
	v_mul_f32_e32 v148, 0xbfb8aa3b, v148
	v_mul_f32_e32 v149, 0xbfb8aa3b, v149
	v_mul_f32_e32 v150, 0xbfb8aa3b, v150
	v_mul_f32_e32 v151, 0xbfb8aa3b, v151
	v_exp_f32_e32 v148, v148
	v_exp_f32_e32 v149, v149
	v_exp_f32_e32 v150, v150
	v_exp_f32_e32 v151, v151
	v_add_f32_e32 v148, 1.0, v148
	v_add_f32_e32 v149, 1.0, v149
	v_add_f32_e32 v150, 1.0, v150
	v_add_f32_e32 v151, 1.0, v151
	v_rcp_f32_e32 v148, v148
	v_rcp_f32_e32 v149, v149
	v_rcp_f32_e32 v150, v150
	v_rcp_f32_e32 v151, v151
	s_nop 0
	v_pk_mul_f32 v[148:149], v[10:11], v[148:149]
	v_pk_mul_f32 v[150:151], v[12:13], v[150:151]
	v_cvt_pk_bf16_f32 v166, v148, v149
	v_cvt_pk_bf16_f32 v167, v150, v151
	s_nop 1
	v_permlane16_swap_b32 v164, v166
	v_permlane16_swap_b32 v165, v167
	s_nop 1
	global_store_dwordx4 v159, v[164:167], s[96:97]
	v_mul_f32_e32 v148, 0x3d372713, v6
	v_mul_f32_e32 v149, 0x3d372713, v7
	v_mul_f32_e32 v150, 0x3d372713, v8
	v_mul_f32_e32 v151, 0x3d372713, v9
	v_mul_f32_e32 v148, v6, v148
	v_mul_f32_e32 v149, v7, v149
	v_mul_f32_e32 v150, v8, v150
	v_mul_f32_e32 v151, v9, v151
	v_fma_f32 v148, v6, v148, v6
	v_fma_f32 v149, v7, v149, v7
	v_fma_f32 v150, v8, v150, v8
	v_fma_f32 v151, v9, v151, v9
	v_mul_f32_e32 v148, 0x3f4c422a, v148
	v_mul_f32_e32 v149, 0x3f4c422a, v149
	v_mul_f32_e32 v150, 0x3f4c422a, v150
	v_mul_f32_e32 v151, 0x3f4c422a, v151
	v_add_f32_e32 v148, v148, v148
	v_add_f32_e32 v149, v149, v149
	v_add_f32_e32 v150, v150, v150
	v_add_f32_e32 v151, v151, v151
	v_mul_f32_e32 v148, 0xbfb8aa3b, v148
	v_mul_f32_e32 v149, 0xbfb8aa3b, v149
	v_mul_f32_e32 v150, 0xbfb8aa3b, v150
	v_mul_f32_e32 v151, 0xbfb8aa3b, v151
	v_exp_f32_e32 v148, v148
	v_exp_f32_e32 v149, v149
	v_exp_f32_e32 v150, v150
	v_exp_f32_e32 v151, v151
	v_add_f32_e32 v148, 1.0, v148
	v_add_f32_e32 v149, 1.0, v149
	v_add_f32_e32 v150, 1.0, v150
	v_add_f32_e32 v151, 1.0, v151
	v_rcp_f32_e32 v148, v148
	v_rcp_f32_e32 v149, v149
	v_rcp_f32_e32 v150, v150
	v_rcp_f32_e32 v151, v151
	s_nop 0
	v_pk_mul_f32 v[148:149], v[6:7], v[148:149]
	v_pk_mul_f32 v[150:151], v[8:9], v[150:151]
	v_cvt_pk_bf16_f32 v168, v148, v149
	v_cvt_pk_bf16_f32 v169, v150, v151
	v_mul_f32_e32 v148, 0x3d372713, v2
	v_mul_f32_e32 v149, 0x3d372713, v3
	v_mul_f32_e32 v150, 0x3d372713, v4
	v_mul_f32_e32 v151, 0x3d372713, v5
	v_mul_f32_e32 v148, v2, v148
	v_mul_f32_e32 v149, v3, v149
	v_mul_f32_e32 v150, v4, v150
	v_mul_f32_e32 v151, v5, v151
	v_fma_f32 v148, v2, v148, v2
	v_fma_f32 v149, v3, v149, v3
	v_fma_f32 v150, v4, v150, v4
	v_fma_f32 v151, v5, v151, v5
	v_mul_f32_e32 v148, 0x3f4c422a, v148
	v_mul_f32_e32 v149, 0x3f4c422a, v149
	v_mul_f32_e32 v150, 0x3f4c422a, v150
	v_mul_f32_e32 v151, 0x3f4c422a, v151
	v_add_f32_e32 v148, v148, v148
	v_add_f32_e32 v149, v149, v149
	v_add_f32_e32 v150, v150, v150
	v_add_f32_e32 v151, v151, v151
	v_mul_f32_e32 v148, 0xbfb8aa3b, v148
	v_mul_f32_e32 v149, 0xbfb8aa3b, v149
	v_mul_f32_e32 v150, 0xbfb8aa3b, v150
	v_mul_f32_e32 v151, 0xbfb8aa3b, v151
	v_exp_f32_e32 v148, v148
	v_exp_f32_e32 v149, v149
	v_exp_f32_e32 v150, v150
	v_exp_f32_e32 v151, v151
	v_add_f32_e32 v148, 1.0, v148
	v_add_f32_e32 v149, 1.0, v149
	v_add_f32_e32 v150, 1.0, v150
	v_add_f32_e32 v151, 1.0, v151
	v_rcp_f32_e32 v148, v148
	v_rcp_f32_e32 v149, v149
	v_rcp_f32_e32 v150, v150
	v_rcp_f32_e32 v151, v151
	s_nop 0
	v_pk_mul_f32 v[148:149], v[2:3], v[148:149]
	v_pk_mul_f32 v[150:151], v[4:5], v[150:151]
	v_cvt_pk_bf16_f32 v170, v148, v149
	v_cvt_pk_bf16_f32 v171, v150, v151
	s_nop 1
	v_permlane16_swap_b32 v168, v170
	v_permlane16_swap_b32 v169, v171
	s_nop 1
	global_store_dwordx4 v159, v[168:171], s[96:97] offset:64
	s_lshl_b32 s2, s49, 17
	s_lshl_b32 s38, s3, 8
	s_add_i32 s2, s2, s38
	s_add_u32 s96, s92, s2
	s_addc_u32 s97, s93, 0
	v_mul_f32_e32 v148, 0x3d372713, v66
	v_mul_f32_e32 v149, 0x3d372713, v67
	v_mul_f32_e32 v150, 0x3d372713, v68
	v_mul_f32_e32 v151, 0x3d372713, v69
	v_mul_f32_e32 v148, v66, v148
	v_mul_f32_e32 v149, v67, v149
	v_mul_f32_e32 v150, v68, v150
	v_mul_f32_e32 v151, v69, v151
	v_fma_f32 v148, v66, v148, v66
	v_fma_f32 v149, v67, v149, v67
	v_fma_f32 v150, v68, v150, v68
	v_fma_f32 v151, v69, v151, v69
	v_mul_f32_e32 v148, 0x3f4c422a, v148
	v_mul_f32_e32 v149, 0x3f4c422a, v149
	v_mul_f32_e32 v150, 0x3f4c422a, v150
	v_mul_f32_e32 v151, 0x3f4c422a, v151
	v_add_f32_e32 v148, v148, v148
	v_add_f32_e32 v149, v149, v149
	v_add_f32_e32 v150, v150, v150
	v_add_f32_e32 v151, v151, v151
	v_mul_f32_e32 v148, 0xbfb8aa3b, v148
	v_mul_f32_e32 v149, 0xbfb8aa3b, v149
	v_mul_f32_e32 v150, 0xbfb8aa3b, v150
	v_mul_f32_e32 v151, 0xbfb8aa3b, v151
	v_exp_f32_e32 v148, v148
	v_exp_f32_e32 v149, v149
	v_exp_f32_e32 v150, v150
	v_exp_f32_e32 v151, v151
	v_add_f32_e32 v148, 1.0, v148
	v_add_f32_e32 v149, 1.0, v149
	v_add_f32_e32 v150, 1.0, v150
	v_add_f32_e32 v151, 1.0, v151
	v_rcp_f32_e32 v148, v148
	v_rcp_f32_e32 v149, v149
	v_rcp_f32_e32 v150, v150
	v_rcp_f32_e32 v151, v151
	s_nop 0
	v_pk_mul_f32 v[148:149], v[66:67], v[148:149]
	v_pk_mul_f32 v[150:151], v[68:69], v[150:151]
	v_cvt_pk_bf16_f32 v164, v148, v149
	v_cvt_pk_bf16_f32 v165, v150, v151
	v_mul_f32_e32 v148, 0x3d372713, v70
	v_mul_f32_e32 v149, 0x3d372713, v71
	v_mul_f32_e32 v150, 0x3d372713, v72
	v_mul_f32_e32 v151, 0x3d372713, v73
	v_mul_f32_e32 v148, v70, v148
	v_mul_f32_e32 v149, v71, v149
	v_mul_f32_e32 v150, v72, v150
	v_mul_f32_e32 v151, v73, v151
	v_fma_f32 v148, v70, v148, v70
	v_fma_f32 v149, v71, v149, v71
	v_fma_f32 v150, v72, v150, v72
	v_fma_f32 v151, v73, v151, v73
	v_mul_f32_e32 v148, 0x3f4c422a, v148
	v_mul_f32_e32 v149, 0x3f4c422a, v149
	v_mul_f32_e32 v150, 0x3f4c422a, v150
	v_mul_f32_e32 v151, 0x3f4c422a, v151
	v_add_f32_e32 v148, v148, v148
	v_add_f32_e32 v149, v149, v149
	v_add_f32_e32 v150, v150, v150
	v_add_f32_e32 v151, v151, v151
	v_mul_f32_e32 v148, 0xbfb8aa3b, v148
	v_mul_f32_e32 v149, 0xbfb8aa3b, v149
	v_mul_f32_e32 v150, 0xbfb8aa3b, v150
	v_mul_f32_e32 v151, 0xbfb8aa3b, v151
	v_exp_f32_e32 v148, v148
	v_exp_f32_e32 v149, v149
	v_exp_f32_e32 v150, v150
	v_exp_f32_e32 v151, v151
	v_add_f32_e32 v148, 1.0, v148
	v_add_f32_e32 v149, 1.0, v149
	v_add_f32_e32 v150, 1.0, v150
	v_add_f32_e32 v151, 1.0, v151
	v_rcp_f32_e32 v148, v148
	v_rcp_f32_e32 v149, v149
	v_rcp_f32_e32 v150, v150
	v_rcp_f32_e32 v151, v151
	s_nop 0
	v_pk_mul_f32 v[148:149], v[70:71], v[148:149]
	v_pk_mul_f32 v[150:151], v[72:73], v[150:151]
	v_cvt_pk_bf16_f32 v166, v148, v149
	v_cvt_pk_bf16_f32 v167, v150, v151
	s_nop 1
	v_permlane16_swap_b32 v164, v166
	v_permlane16_swap_b32 v165, v167
	s_nop 1
	global_store_dwordx4 v156, v[164:167], s[96:97]
	v_mul_f32_e32 v148, 0x3d372713, v82
	v_mul_f32_e32 v149, 0x3d372713, v83
	v_mul_f32_e32 v150, 0x3d372713, v84
	v_mul_f32_e32 v151, 0x3d372713, v85
	v_mul_f32_e32 v148, v82, v148
	v_mul_f32_e32 v149, v83, v149
	v_mul_f32_e32 v150, v84, v150
	v_mul_f32_e32 v151, v85, v151
	v_fma_f32 v148, v82, v148, v82
	v_fma_f32 v149, v83, v149, v83
	v_fma_f32 v150, v84, v150, v84
	v_fma_f32 v151, v85, v151, v85
	v_mul_f32_e32 v148, 0x3f4c422a, v148
	v_mul_f32_e32 v149, 0x3f4c422a, v149
	v_mul_f32_e32 v150, 0x3f4c422a, v150
	v_mul_f32_e32 v151, 0x3f4c422a, v151
	v_add_f32_e32 v148, v148, v148
	v_add_f32_e32 v149, v149, v149
	v_add_f32_e32 v150, v150, v150
	v_add_f32_e32 v151, v151, v151
	v_mul_f32_e32 v148, 0xbfb8aa3b, v148
	v_mul_f32_e32 v149, 0xbfb8aa3b, v149
	v_mul_f32_e32 v150, 0xbfb8aa3b, v150
	v_mul_f32_e32 v151, 0xbfb8aa3b, v151
	v_exp_f32_e32 v148, v148
	v_exp_f32_e32 v149, v149
	v_exp_f32_e32 v150, v150
	v_exp_f32_e32 v151, v151
	v_add_f32_e32 v148, 1.0, v148
	v_add_f32_e32 v149, 1.0, v149
	v_add_f32_e32 v150, 1.0, v150
	v_add_f32_e32 v151, 1.0, v151
	v_rcp_f32_e32 v148, v148
	v_rcp_f32_e32 v149, v149
	v_rcp_f32_e32 v150, v150
	v_rcp_f32_e32 v151, v151
	s_nop 0
	v_pk_mul_f32 v[148:149], v[82:83], v[148:149]
	v_pk_mul_f32 v[150:151], v[84:85], v[150:151]
	v_cvt_pk_bf16_f32 v168, v148, v149
	v_cvt_pk_bf16_f32 v169, v150, v151
	v_mul_f32_e32 v148, 0x3d372713, v88
	v_mul_f32_e32 v149, 0x3d372713, v89
	v_mul_f32_e32 v150, 0x3d372713, v90
	v_mul_f32_e32 v151, 0x3d372713, v91
	v_mul_f32_e32 v148, v88, v148
	v_mul_f32_e32 v149, v89, v149
	v_mul_f32_e32 v150, v90, v150
	v_mul_f32_e32 v151, v91, v151
	v_fma_f32 v148, v88, v148, v88
	v_fma_f32 v149, v89, v149, v89
	v_fma_f32 v150, v90, v150, v90
	v_fma_f32 v151, v91, v151, v91
	v_mul_f32_e32 v148, 0x3f4c422a, v148
	v_mul_f32_e32 v149, 0x3f4c422a, v149
	v_mul_f32_e32 v150, 0x3f4c422a, v150
	v_mul_f32_e32 v151, 0x3f4c422a, v151
	v_add_f32_e32 v148, v148, v148
	v_add_f32_e32 v149, v149, v149
	v_add_f32_e32 v150, v150, v150
	v_add_f32_e32 v151, v151, v151
	v_mul_f32_e32 v148, 0xbfb8aa3b, v148
	v_mul_f32_e32 v149, 0xbfb8aa3b, v149
	v_mul_f32_e32 v150, 0xbfb8aa3b, v150
	v_mul_f32_e32 v151, 0xbfb8aa3b, v151
	v_exp_f32_e32 v148, v148
	v_exp_f32_e32 v149, v149
	v_exp_f32_e32 v150, v150
	v_exp_f32_e32 v151, v151
	v_add_f32_e32 v148, 1.0, v148
	v_add_f32_e32 v149, 1.0, v149
	v_add_f32_e32 v150, 1.0, v150
	v_add_f32_e32 v151, 1.0, v151
	v_rcp_f32_e32 v148, v148
	v_rcp_f32_e32 v149, v149
	v_rcp_f32_e32 v150, v150
	v_rcp_f32_e32 v151, v151
	s_nop 0
	v_pk_mul_f32 v[148:149], v[88:89], v[148:149]
	v_pk_mul_f32 v[150:151], v[90:91], v[150:151]
	v_cvt_pk_bf16_f32 v170, v148, v149
	v_cvt_pk_bf16_f32 v171, v150, v151
	s_nop 1
	v_permlane16_swap_b32 v168, v170
	v_permlane16_swap_b32 v169, v171
	s_nop 1
	global_store_dwordx4 v156, v[168:171], s[96:97] offset:64
	v_mul_f32_e32 v148, 0x3d372713, v92
	v_mul_f32_e32 v149, 0x3d372713, v93
	v_mul_f32_e32 v150, 0x3d372713, v94
	v_mul_f32_e32 v151, 0x3d372713, v95
	v_mul_f32_e32 v148, v92, v148
	v_mul_f32_e32 v149, v93, v149
	v_mul_f32_e32 v150, v94, v150
	v_mul_f32_e32 v151, v95, v151
	v_fma_f32 v148, v92, v148, v92
	v_fma_f32 v149, v93, v149, v93
	v_fma_f32 v150, v94, v150, v94
	v_fma_f32 v151, v95, v151, v95
	v_mul_f32_e32 v148, 0x3f4c422a, v148
	v_mul_f32_e32 v149, 0x3f4c422a, v149
	v_mul_f32_e32 v150, 0x3f4c422a, v150
	v_mul_f32_e32 v151, 0x3f4c422a, v151
	v_add_f32_e32 v148, v148, v148
	v_add_f32_e32 v149, v149, v149
	v_add_f32_e32 v150, v150, v150
	v_add_f32_e32 v151, v151, v151
	v_mul_f32_e32 v148, 0xbfb8aa3b, v148
	v_mul_f32_e32 v149, 0xbfb8aa3b, v149
	v_mul_f32_e32 v150, 0xbfb8aa3b, v150
	v_mul_f32_e32 v151, 0xbfb8aa3b, v151
	v_exp_f32_e32 v148, v148
	v_exp_f32_e32 v149, v149
	v_exp_f32_e32 v150, v150
	v_exp_f32_e32 v151, v151
	v_add_f32_e32 v148, 1.0, v148
	v_add_f32_e32 v149, 1.0, v149
	v_add_f32_e32 v150, 1.0, v150
	v_add_f32_e32 v151, 1.0, v151
	v_rcp_f32_e32 v148, v148
	v_rcp_f32_e32 v149, v149
	v_rcp_f32_e32 v150, v150
	v_rcp_f32_e32 v151, v151
	s_nop 0
	v_pk_mul_f32 v[148:149], v[92:93], v[148:149]
	v_pk_mul_f32 v[150:151], v[94:95], v[150:151]
	v_cvt_pk_bf16_f32 v164, v148, v149
	v_cvt_pk_bf16_f32 v165, v150, v151
	v_mul_f32_e32 v148, 0x3d372713, v96
	v_mul_f32_e32 v149, 0x3d372713, v97
	v_mul_f32_e32 v150, 0x3d372713, v98
	v_mul_f32_e32 v151, 0x3d372713, v99
	v_mul_f32_e32 v148, v96, v148
	v_mul_f32_e32 v149, v97, v149
	v_mul_f32_e32 v150, v98, v150
	v_mul_f32_e32 v151, v99, v151
	v_fma_f32 v148, v96, v148, v96
	v_fma_f32 v149, v97, v149, v97
	v_fma_f32 v150, v98, v150, v98
	v_fma_f32 v151, v99, v151, v99
	v_mul_f32_e32 v148, 0x3f4c422a, v148
	v_mul_f32_e32 v149, 0x3f4c422a, v149
	v_mul_f32_e32 v150, 0x3f4c422a, v150
	v_mul_f32_e32 v151, 0x3f4c422a, v151
	v_add_f32_e32 v148, v148, v148
	v_add_f32_e32 v149, v149, v149
	v_add_f32_e32 v150, v150, v150
	v_add_f32_e32 v151, v151, v151
	v_mul_f32_e32 v148, 0xbfb8aa3b, v148
	v_mul_f32_e32 v149, 0xbfb8aa3b, v149
	v_mul_f32_e32 v150, 0xbfb8aa3b, v150
	v_mul_f32_e32 v151, 0xbfb8aa3b, v151
	v_exp_f32_e32 v148, v148
	v_exp_f32_e32 v149, v149
	v_exp_f32_e32 v150, v150
	v_exp_f32_e32 v151, v151
	v_add_f32_e32 v148, 1.0, v148
	v_add_f32_e32 v149, 1.0, v149
	v_add_f32_e32 v150, 1.0, v150
	v_add_f32_e32 v151, 1.0, v151
	v_rcp_f32_e32 v148, v148
	v_rcp_f32_e32 v149, v149
	v_rcp_f32_e32 v150, v150
	v_rcp_f32_e32 v151, v151
	s_nop 0
	v_pk_mul_f32 v[148:149], v[96:97], v[148:149]
	v_pk_mul_f32 v[150:151], v[98:99], v[150:151]
	v_cvt_pk_bf16_f32 v166, v148, v149
	v_cvt_pk_bf16_f32 v167, v150, v151
	s_nop 1
	v_permlane16_swap_b32 v164, v166
	v_permlane16_swap_b32 v165, v167
	s_nop 1
	global_store_dwordx4 v157, v[164:167], s[96:97]
	v_mul_f32_e32 v148, 0x3d372713, v100
	v_mul_f32_e32 v149, 0x3d372713, v101
	v_mul_f32_e32 v150, 0x3d372713, v102
	v_mul_f32_e32 v151, 0x3d372713, v103
	v_mul_f32_e32 v148, v100, v148
	v_mul_f32_e32 v149, v101, v149
	v_mul_f32_e32 v150, v102, v150
	v_mul_f32_e32 v151, v103, v151
	v_fma_f32 v148, v100, v148, v100
	v_fma_f32 v149, v101, v149, v101
	v_fma_f32 v150, v102, v150, v102
	v_fma_f32 v151, v103, v151, v103
	v_mul_f32_e32 v148, 0x3f4c422a, v148
	v_mul_f32_e32 v149, 0x3f4c422a, v149
	v_mul_f32_e32 v150, 0x3f4c422a, v150
	v_mul_f32_e32 v151, 0x3f4c422a, v151
	v_add_f32_e32 v148, v148, v148
	v_add_f32_e32 v149, v149, v149
	v_add_f32_e32 v150, v150, v150
	v_add_f32_e32 v151, v151, v151
	v_mul_f32_e32 v148, 0xbfb8aa3b, v148
	v_mul_f32_e32 v149, 0xbfb8aa3b, v149
	v_mul_f32_e32 v150, 0xbfb8aa3b, v150
	v_mul_f32_e32 v151, 0xbfb8aa3b, v151
	v_exp_f32_e32 v148, v148
	v_exp_f32_e32 v149, v149
	v_exp_f32_e32 v150, v150
	v_exp_f32_e32 v151, v151
	v_add_f32_e32 v148, 1.0, v148
	v_add_f32_e32 v149, 1.0, v149
	v_add_f32_e32 v150, 1.0, v150
	v_add_f32_e32 v151, 1.0, v151
	v_rcp_f32_e32 v148, v148
	v_rcp_f32_e32 v149, v149
	v_rcp_f32_e32 v150, v150
	v_rcp_f32_e32 v151, v151
	s_nop 0
	v_pk_mul_f32 v[148:149], v[100:101], v[148:149]
	v_pk_mul_f32 v[150:151], v[102:103], v[150:151]
	v_cvt_pk_bf16_f32 v168, v148, v149
	v_cvt_pk_bf16_f32 v169, v150, v151
	v_mul_f32_e32 v148, 0x3d372713, v106
	v_mul_f32_e32 v149, 0x3d372713, v107
	v_mul_f32_e32 v150, 0x3d372713, v108
	v_mul_f32_e32 v151, 0x3d372713, v109
	v_mul_f32_e32 v148, v106, v148
	v_mul_f32_e32 v149, v107, v149
	v_mul_f32_e32 v150, v108, v150
	v_mul_f32_e32 v151, v109, v151
	v_fma_f32 v148, v106, v148, v106
	v_fma_f32 v149, v107, v149, v107
	v_fma_f32 v150, v108, v150, v108
	v_fma_f32 v151, v109, v151, v109
	v_mul_f32_e32 v148, 0x3f4c422a, v148
	v_mul_f32_e32 v149, 0x3f4c422a, v149
	v_mul_f32_e32 v150, 0x3f4c422a, v150
	v_mul_f32_e32 v151, 0x3f4c422a, v151
	v_add_f32_e32 v148, v148, v148
	v_add_f32_e32 v149, v149, v149
	v_add_f32_e32 v150, v150, v150
	v_add_f32_e32 v151, v151, v151
	v_mul_f32_e32 v148, 0xbfb8aa3b, v148
	v_mul_f32_e32 v149, 0xbfb8aa3b, v149
	v_mul_f32_e32 v150, 0xbfb8aa3b, v150
	v_mul_f32_e32 v151, 0xbfb8aa3b, v151
	v_exp_f32_e32 v148, v148
	v_exp_f32_e32 v149, v149
	v_exp_f32_e32 v150, v150
	v_exp_f32_e32 v151, v151
	v_add_f32_e32 v148, 1.0, v148
	v_add_f32_e32 v149, 1.0, v149
	v_add_f32_e32 v150, 1.0, v150
	v_add_f32_e32 v151, 1.0, v151
	v_rcp_f32_e32 v148, v148
	v_rcp_f32_e32 v149, v149
	v_rcp_f32_e32 v150, v150
	v_rcp_f32_e32 v151, v151
	s_nop 0
	v_pk_mul_f32 v[148:149], v[106:107], v[148:149]
	v_pk_mul_f32 v[150:151], v[108:109], v[150:151]
	v_cvt_pk_bf16_f32 v170, v148, v149
	v_cvt_pk_bf16_f32 v171, v150, v151
	s_nop 1
	v_permlane16_swap_b32 v168, v170
	v_permlane16_swap_b32 v169, v171
	s_nop 1
	global_store_dwordx4 v157, v[168:171], s[96:97] offset:64
	v_mul_f32_e32 v148, 0x3d372713, v110
	v_mul_f32_e32 v149, 0x3d372713, v111
	v_mul_f32_e32 v150, 0x3d372713, v112
	v_mul_f32_e32 v151, 0x3d372713, v113
	v_mul_f32_e32 v148, v110, v148
	v_mul_f32_e32 v149, v111, v149
	v_mul_f32_e32 v150, v112, v150
	v_mul_f32_e32 v151, v113, v151
	v_fma_f32 v148, v110, v148, v110
	v_fma_f32 v149, v111, v149, v111
	v_fma_f32 v150, v112, v150, v112
	v_fma_f32 v151, v113, v151, v113
	v_mul_f32_e32 v148, 0x3f4c422a, v148
	v_mul_f32_e32 v149, 0x3f4c422a, v149
	v_mul_f32_e32 v150, 0x3f4c422a, v150
	v_mul_f32_e32 v151, 0x3f4c422a, v151
	v_add_f32_e32 v148, v148, v148
	v_add_f32_e32 v149, v149, v149
	v_add_f32_e32 v150, v150, v150
	v_add_f32_e32 v151, v151, v151
	v_mul_f32_e32 v148, 0xbfb8aa3b, v148
	v_mul_f32_e32 v149, 0xbfb8aa3b, v149
	v_mul_f32_e32 v150, 0xbfb8aa3b, v150
	v_mul_f32_e32 v151, 0xbfb8aa3b, v151
	v_exp_f32_e32 v148, v148
	v_exp_f32_e32 v149, v149
	v_exp_f32_e32 v150, v150
	v_exp_f32_e32 v151, v151
	v_add_f32_e32 v148, 1.0, v148
	v_add_f32_e32 v149, 1.0, v149
	v_add_f32_e32 v150, 1.0, v150
	v_add_f32_e32 v151, 1.0, v151
	v_rcp_f32_e32 v148, v148
	v_rcp_f32_e32 v149, v149
	v_rcp_f32_e32 v150, v150
	v_rcp_f32_e32 v151, v151
	s_nop 0
	v_pk_mul_f32 v[148:149], v[110:111], v[148:149]
	v_pk_mul_f32 v[150:151], v[112:113], v[150:151]
	v_cvt_pk_bf16_f32 v164, v148, v149
	v_cvt_pk_bf16_f32 v165, v150, v151
	v_mul_f32_e32 v148, 0x3d372713, v114
	v_mul_f32_e32 v149, 0x3d372713, v115
	v_mul_f32_e32 v150, 0x3d372713, v116
	v_mul_f32_e32 v151, 0x3d372713, v117
	v_mul_f32_e32 v148, v114, v148
	v_mul_f32_e32 v149, v115, v149
	v_mul_f32_e32 v150, v116, v150
	v_mul_f32_e32 v151, v117, v151
	v_fma_f32 v148, v114, v148, v114
	v_fma_f32 v149, v115, v149, v115
	v_fma_f32 v150, v116, v150, v116
	v_fma_f32 v151, v117, v151, v117
	v_mul_f32_e32 v148, 0x3f4c422a, v148
	v_mul_f32_e32 v149, 0x3f4c422a, v149
	v_mul_f32_e32 v150, 0x3f4c422a, v150
	v_mul_f32_e32 v151, 0x3f4c422a, v151
	v_add_f32_e32 v148, v148, v148
	v_add_f32_e32 v149, v149, v149
	v_add_f32_e32 v150, v150, v150
	v_add_f32_e32 v151, v151, v151
	v_mul_f32_e32 v148, 0xbfb8aa3b, v148
	v_mul_f32_e32 v149, 0xbfb8aa3b, v149
	v_mul_f32_e32 v150, 0xbfb8aa3b, v150
	v_mul_f32_e32 v151, 0xbfb8aa3b, v151
	v_exp_f32_e32 v148, v148
	v_exp_f32_e32 v149, v149
	v_exp_f32_e32 v150, v150
	v_exp_f32_e32 v151, v151
	v_add_f32_e32 v148, 1.0, v148
	v_add_f32_e32 v149, 1.0, v149
	v_add_f32_e32 v150, 1.0, v150
	v_add_f32_e32 v151, 1.0, v151
	v_rcp_f32_e32 v148, v148
	v_rcp_f32_e32 v149, v149
	v_rcp_f32_e32 v150, v150
	v_rcp_f32_e32 v151, v151
	s_nop 0
	v_pk_mul_f32 v[148:149], v[114:115], v[148:149]
	v_pk_mul_f32 v[150:151], v[116:117], v[150:151]
	v_cvt_pk_bf16_f32 v166, v148, v149
	v_cvt_pk_bf16_f32 v167, v150, v151
	s_nop 1
	v_permlane16_swap_b32 v164, v166
	v_permlane16_swap_b32 v165, v167
	s_nop 1
	global_store_dwordx4 v158, v[164:167], s[96:97]
	v_mul_f32_e32 v148, 0x3d372713, v118
	v_mul_f32_e32 v149, 0x3d372713, v119
	v_mul_f32_e32 v150, 0x3d372713, v120
	v_mul_f32_e32 v151, 0x3d372713, v121
	v_mul_f32_e32 v148, v118, v148
	v_mul_f32_e32 v149, v119, v149
	v_mul_f32_e32 v150, v120, v150
	v_mul_f32_e32 v151, v121, v151
	v_fma_f32 v148, v118, v148, v118
	v_fma_f32 v149, v119, v149, v119
	v_fma_f32 v150, v120, v150, v120
	v_fma_f32 v151, v121, v151, v121
	v_mul_f32_e32 v148, 0x3f4c422a, v148
	v_mul_f32_e32 v149, 0x3f4c422a, v149
	v_mul_f32_e32 v150, 0x3f4c422a, v150
	v_mul_f32_e32 v151, 0x3f4c422a, v151
	v_add_f32_e32 v148, v148, v148
	v_add_f32_e32 v149, v149, v149
	v_add_f32_e32 v150, v150, v150
	v_add_f32_e32 v151, v151, v151
	v_mul_f32_e32 v148, 0xbfb8aa3b, v148
	v_mul_f32_e32 v149, 0xbfb8aa3b, v149
	v_mul_f32_e32 v150, 0xbfb8aa3b, v150
	v_mul_f32_e32 v151, 0xbfb8aa3b, v151
	v_exp_f32_e32 v148, v148
	v_exp_f32_e32 v149, v149
	v_exp_f32_e32 v150, v150
	v_exp_f32_e32 v151, v151
	v_add_f32_e32 v148, 1.0, v148
	v_add_f32_e32 v149, 1.0, v149
	v_add_f32_e32 v150, 1.0, v150
	v_add_f32_e32 v151, 1.0, v151
	v_rcp_f32_e32 v148, v148
	v_rcp_f32_e32 v149, v149
	v_rcp_f32_e32 v150, v150
	v_rcp_f32_e32 v151, v151
	s_nop 0
	v_pk_mul_f32 v[148:149], v[118:119], v[148:149]
	v_pk_mul_f32 v[150:151], v[120:121], v[150:151]
	v_cvt_pk_bf16_f32 v168, v148, v149
	v_cvt_pk_bf16_f32 v169, v150, v151
	v_mul_f32_e32 v148, 0x3d372713, v122
	v_mul_f32_e32 v149, 0x3d372713, v123
	v_mul_f32_e32 v150, 0x3d372713, v124
	v_mul_f32_e32 v151, 0x3d372713, v125
	v_mul_f32_e32 v148, v122, v148
	v_mul_f32_e32 v149, v123, v149
	v_mul_f32_e32 v150, v124, v150
	v_mul_f32_e32 v151, v125, v151
	v_fma_f32 v148, v122, v148, v122
	v_fma_f32 v149, v123, v149, v123
	v_fma_f32 v150, v124, v150, v124
	v_fma_f32 v151, v125, v151, v125
	v_mul_f32_e32 v148, 0x3f4c422a, v148
	v_mul_f32_e32 v149, 0x3f4c422a, v149
	v_mul_f32_e32 v150, 0x3f4c422a, v150
	v_mul_f32_e32 v151, 0x3f4c422a, v151
	v_add_f32_e32 v148, v148, v148
	v_add_f32_e32 v149, v149, v149
	v_add_f32_e32 v150, v150, v150
	v_add_f32_e32 v151, v151, v151
	v_mul_f32_e32 v148, 0xbfb8aa3b, v148
	v_mul_f32_e32 v149, 0xbfb8aa3b, v149
	v_mul_f32_e32 v150, 0xbfb8aa3b, v150
	v_mul_f32_e32 v151, 0xbfb8aa3b, v151
	v_exp_f32_e32 v148, v148
	v_exp_f32_e32 v149, v149
	v_exp_f32_e32 v150, v150
	v_exp_f32_e32 v151, v151
	v_add_f32_e32 v148, 1.0, v148
	v_add_f32_e32 v149, 1.0, v149
	v_add_f32_e32 v150, 1.0, v150
	v_add_f32_e32 v151, 1.0, v151
	v_rcp_f32_e32 v148, v148
	v_rcp_f32_e32 v149, v149
	v_rcp_f32_e32 v150, v150
	v_rcp_f32_e32 v151, v151
	s_nop 0
	v_pk_mul_f32 v[148:149], v[122:123], v[148:149]
	v_pk_mul_f32 v[150:151], v[124:125], v[150:151]
	v_cvt_pk_bf16_f32 v170, v148, v149
	v_cvt_pk_bf16_f32 v171, v150, v151
	s_nop 1
	v_permlane16_swap_b32 v168, v170
	v_permlane16_swap_b32 v169, v171
	s_nop 1
	global_store_dwordx4 v158, v[168:171], s[96:97] offset:64
	v_mul_f32_e32 v148, 0x3d372713, v126
	v_mul_f32_e32 v149, 0x3d372713, v127
	v_mul_f32_e32 v150, 0x3d372713, v128
	v_mul_f32_e32 v151, 0x3d372713, v129
	v_mul_f32_e32 v148, v126, v148
	v_mul_f32_e32 v149, v127, v149
	v_mul_f32_e32 v150, v128, v150
	v_mul_f32_e32 v151, v129, v151
	v_fma_f32 v148, v126, v148, v126
	v_fma_f32 v149, v127, v149, v127
	v_fma_f32 v150, v128, v150, v128
	v_fma_f32 v151, v129, v151, v129
	v_mul_f32_e32 v148, 0x3f4c422a, v148
	v_mul_f32_e32 v149, 0x3f4c422a, v149
	v_mul_f32_e32 v150, 0x3f4c422a, v150
	v_mul_f32_e32 v151, 0x3f4c422a, v151
	v_add_f32_e32 v148, v148, v148
	v_add_f32_e32 v149, v149, v149
	v_add_f32_e32 v150, v150, v150
	v_add_f32_e32 v151, v151, v151
	v_mul_f32_e32 v148, 0xbfb8aa3b, v148
	v_mul_f32_e32 v149, 0xbfb8aa3b, v149
	v_mul_f32_e32 v150, 0xbfb8aa3b, v150
	v_mul_f32_e32 v151, 0xbfb8aa3b, v151
	v_exp_f32_e32 v148, v148
	v_exp_f32_e32 v149, v149
	v_exp_f32_e32 v150, v150
	v_exp_f32_e32 v151, v151
	v_add_f32_e32 v148, 1.0, v148
	v_add_f32_e32 v149, 1.0, v149
	v_add_f32_e32 v150, 1.0, v150
	v_add_f32_e32 v151, 1.0, v151
	v_rcp_f32_e32 v148, v148
	v_rcp_f32_e32 v149, v149
	v_rcp_f32_e32 v150, v150
	v_rcp_f32_e32 v151, v151
	s_nop 0
	v_pk_mul_f32 v[148:149], v[126:127], v[148:149]
	v_pk_mul_f32 v[150:151], v[128:129], v[150:151]
	v_cvt_pk_bf16_f32 v164, v148, v149
	v_cvt_pk_bf16_f32 v165, v150, v151
	v_mul_f32_e32 v148, 0x3d372713, v136
	v_mul_f32_e32 v149, 0x3d372713, v137
	v_mul_f32_e32 v150, 0x3d372713, v138
	v_mul_f32_e32 v151, 0x3d372713, v139
	v_mul_f32_e32 v148, v136, v148
	v_mul_f32_e32 v149, v137, v149
	v_mul_f32_e32 v150, v138, v150
	v_mul_f32_e32 v151, v139, v151
	v_fma_f32 v148, v136, v148, v136
	v_fma_f32 v149, v137, v149, v137
	v_fma_f32 v150, v138, v150, v138
	v_fma_f32 v151, v139, v151, v139
	v_mul_f32_e32 v148, 0x3f4c422a, v148
	v_mul_f32_e32 v149, 0x3f4c422a, v149
	v_mul_f32_e32 v150, 0x3f4c422a, v150
	v_mul_f32_e32 v151, 0x3f4c422a, v151
	v_add_f32_e32 v148, v148, v148
	v_add_f32_e32 v149, v149, v149
	v_add_f32_e32 v150, v150, v150
	v_add_f32_e32 v151, v151, v151
	v_mul_f32_e32 v148, 0xbfb8aa3b, v148
	v_mul_f32_e32 v149, 0xbfb8aa3b, v149
	v_mul_f32_e32 v150, 0xbfb8aa3b, v150
	v_mul_f32_e32 v151, 0xbfb8aa3b, v151
	v_exp_f32_e32 v148, v148
	v_exp_f32_e32 v149, v149
	v_exp_f32_e32 v150, v150
	v_exp_f32_e32 v151, v151
	v_add_f32_e32 v148, 1.0, v148
	v_add_f32_e32 v149, 1.0, v149
	v_add_f32_e32 v150, 1.0, v150
	v_add_f32_e32 v151, 1.0, v151
	v_rcp_f32_e32 v148, v148
	v_rcp_f32_e32 v149, v149
	v_rcp_f32_e32 v150, v150
	v_rcp_f32_e32 v151, v151
	s_nop 0
	v_pk_mul_f32 v[148:149], v[136:137], v[148:149]
	v_pk_mul_f32 v[150:151], v[138:139], v[150:151]
	v_cvt_pk_bf16_f32 v166, v148, v149
	v_cvt_pk_bf16_f32 v167, v150, v151
	s_nop 1
	v_permlane16_swap_b32 v164, v166
	v_permlane16_swap_b32 v165, v167
	s_nop 1
	global_store_dwordx4 v159, v[164:167], s[96:97]
	v_mul_f32_e32 v148, 0x3d372713, v140
	v_mul_f32_e32 v149, 0x3d372713, v141
	v_mul_f32_e32 v150, 0x3d372713, v142
	v_mul_f32_e32 v151, 0x3d372713, v143
	v_mul_f32_e32 v148, v140, v148
	v_mul_f32_e32 v149, v141, v149
	v_mul_f32_e32 v150, v142, v150
	v_mul_f32_e32 v151, v143, v151
	v_fma_f32 v148, v140, v148, v140
	v_fma_f32 v149, v141, v149, v141
	v_fma_f32 v150, v142, v150, v142
	v_fma_f32 v151, v143, v151, v143
	v_mul_f32_e32 v148, 0x3f4c422a, v148
	v_mul_f32_e32 v149, 0x3f4c422a, v149
	v_mul_f32_e32 v150, 0x3f4c422a, v150
	v_mul_f32_e32 v151, 0x3f4c422a, v151
	v_add_f32_e32 v148, v148, v148
	v_add_f32_e32 v149, v149, v149
	v_add_f32_e32 v150, v150, v150
	v_add_f32_e32 v151, v151, v151
	v_mul_f32_e32 v148, 0xbfb8aa3b, v148
	v_mul_f32_e32 v149, 0xbfb8aa3b, v149
	v_mul_f32_e32 v150, 0xbfb8aa3b, v150
	v_mul_f32_e32 v151, 0xbfb8aa3b, v151
	v_exp_f32_e32 v148, v148
	v_exp_f32_e32 v149, v149
	v_exp_f32_e32 v150, v150
	v_exp_f32_e32 v151, v151
	v_add_f32_e32 v148, 1.0, v148
	v_add_f32_e32 v149, 1.0, v149
	v_add_f32_e32 v150, 1.0, v150
	v_add_f32_e32 v151, 1.0, v151
	v_rcp_f32_e32 v148, v148
	v_rcp_f32_e32 v149, v149
	v_rcp_f32_e32 v150, v150
	v_rcp_f32_e32 v151, v151
	s_nop 0
	v_pk_mul_f32 v[148:149], v[140:141], v[148:149]
	v_pk_mul_f32 v[150:151], v[142:143], v[150:151]
	v_cvt_pk_bf16_f32 v168, v148, v149
	v_cvt_pk_bf16_f32 v169, v150, v151
	v_mul_f32_e32 v148, 0x3d372713, v144
	v_mul_f32_e32 v149, 0x3d372713, v145
	v_mul_f32_e32 v150, 0x3d372713, v146
	v_mul_f32_e32 v151, 0x3d372713, v147
	v_mul_f32_e32 v148, v144, v148
	v_mul_f32_e32 v149, v145, v149
	v_mul_f32_e32 v150, v146, v150
	v_mul_f32_e32 v151, v147, v151
	v_fma_f32 v148, v144, v148, v144
	v_fma_f32 v149, v145, v149, v145
	v_fma_f32 v150, v146, v150, v146
	v_fma_f32 v151, v147, v151, v147
	v_mul_f32_e32 v148, 0x3f4c422a, v148
	v_mul_f32_e32 v149, 0x3f4c422a, v149
	v_mul_f32_e32 v150, 0x3f4c422a, v150
	v_mul_f32_e32 v151, 0x3f4c422a, v151
	v_add_f32_e32 v148, v148, v148
	v_add_f32_e32 v149, v149, v149
	v_add_f32_e32 v150, v150, v150
	v_add_f32_e32 v151, v151, v151
	v_mul_f32_e32 v148, 0xbfb8aa3b, v148
	v_mul_f32_e32 v149, 0xbfb8aa3b, v149
	v_mul_f32_e32 v150, 0xbfb8aa3b, v150
	v_mul_f32_e32 v151, 0xbfb8aa3b, v151
	v_exp_f32_e32 v148, v148
	v_exp_f32_e32 v149, v149
	v_exp_f32_e32 v150, v150
	v_exp_f32_e32 v151, v151
	v_add_f32_e32 v148, 1.0, v148
	v_add_f32_e32 v149, 1.0, v149
	v_add_f32_e32 v150, 1.0, v150
	v_add_f32_e32 v151, 1.0, v151
	v_rcp_f32_e32 v148, v148
	v_rcp_f32_e32 v149, v149
	v_rcp_f32_e32 v150, v150
	v_rcp_f32_e32 v151, v151
	s_nop 0
	v_pk_mul_f32 v[148:149], v[144:145], v[148:149]
	v_pk_mul_f32 v[150:151], v[146:147], v[150:151]
	v_cvt_pk_bf16_f32 v170, v148, v149
	v_cvt_pk_bf16_f32 v171, v150, v151
	s_nop 1
	v_permlane16_swap_b32 v168, v170
	v_permlane16_swap_b32 v169, v171
	s_nop 1
	global_store_dwordx4 v159, v[168:171], s[96:97] offset:64
	s_branch .Lg2_next
